# P1 entry row-scale table: the per-unit rs0 loads all issued first, one wait, then the LDS writes (was load-wait-write per unit)
# speedup vs baseline: 1.0029x; 1.0029x over previous
.LBB0_211:
	s_and_saveexec_b64 s[12:13], s[4:5]
	s_cbranch_execz .LBB0_213
	s_ashr_i32 s14, s14, 3
	s_add_i32 s14, s15, s14
	s_ashr_i32 s15, s14, 31
	s_lshr_b32 s15, s15, 26
	s_add_i32 s15, s14, s15
	s_and_b32 s18, s15, 0xffc0
	s_sub_i32 s14, s14, s18
	s_bfe_i32 s18, s14, 0x80000
	s_bfe_u32 s18, s18, 0x3000c
	s_add_i32 s18, s14, s18
	s_and_b32 s18, s18, 0xf8
	s_sub_i32 s14, s14, s18
	s_sext_i32_i8 s14, s14
	s_lshl_b32 s15, s15, 5
	s_and_b32 s15, s15, 0xfffff800
	s_lshl_b32 s14, s14, 8
	s_add_i32 s15, s15, s14
	v_or_b32_e32 v2, s15, v0
	v_ashrrev_i32_e32 v3, 31, v2
	v_lshl_add_u64 v[2:3], v[2:3], 2, s[6:7]
	global_load_dword v200, v[2:3], off

.LBB0_219:
	s_and_saveexec_b64 s[14:15], s[4:5]
	s_cbranch_execz .LBB0_221
	s_ashr_i32 s18, s18, 3
	s_add_i32 s18, s19, s18
	s_ashr_i32 s19, s18, 31
	s_lshr_b32 s19, s19, 26
	s_add_i32 s19, s18, s19
	s_ashr_i32 s20, s19, 6
	s_lshl_b32 s20, s20, 3
	s_sub_i32 s21, 0x80, s20
	s_min_i32 s21, s21, 8
	s_abs_i32 s21, s21
	v_cvt_f32_u32_e32 v4, s21
	s_sub_i32 s22, 0, s21
	s_andn2_b32 s19, s19, 63
	s_sub_i32 s18, s18, s19
	v_rcp_iflag_f32_e32 v4, v4
	s_ashr_i32 s19, s18, 31
	s_abs_i32 s18, s18
	v_mul_f32_e32 v4, 0x4f7ffffe, v4
	v_cvt_u32_f32_e32 v4, v4
	s_nop 0
	v_readfirstlane_b32 s23, v4
	s_mul_i32 s22, s22, s23
	s_mul_hi_u32 s22, s23, s22
	s_add_i32 s23, s23, s22
	s_mul_hi_u32 s22, s18, s23
	s_mul_i32 s22, s22, s21
	s_sub_i32 s18, s18, s22
	s_sub_i32 s22, s18, s21
	s_cmp_ge_u32 s18, s21
	s_cselect_b32 s18, s22, s18
	s_sub_i32 s22, s18, s21
	s_cmp_ge_u32 s18, s21
	s_cselect_b32 s18, s22, s18
	s_xor_b32 s18, s18, s19
	s_sub_i32 s18, s18, s19
	s_add_i32 s20, s20, s18
	v_lshl_or_b32 v4, s20, 8, v0
	v_ashrrev_i32_e32 v5, 31, v4
	v_lshl_add_u64 v[4:5], v[4:5], 2, s[6:7]
	global_load_dword v201, v[4:5], off

.LBB0_227:
	s_and_saveexec_b64 s[14:15], s[4:5]
	s_cbranch_execz .LBB0_229
	s_ashr_i32 s18, s18, 3
	s_add_i32 s18, s19, s18
	s_ashr_i32 s19, s18, 31
	s_lshr_b32 s19, s19, 26
	s_add_i32 s19, s18, s19
	s_ashr_i32 s20, s19, 6
	s_lshl_b32 s20, s20, 3
	s_sub_i32 s21, 0x80, s20
	s_min_i32 s21, s21, 8
	s_abs_i32 s21, s21
	v_cvt_f32_u32_e32 v2, s21
	s_sub_i32 s22, 0, s21
	s_andn2_b32 s19, s19, 63
	s_sub_i32 s18, s18, s19
	v_rcp_iflag_f32_e32 v2, v2
	s_ashr_i32 s19, s18, 31
	s_abs_i32 s18, s18
	v_mul_f32_e32 v2, 0x4f7ffffe, v2
	v_cvt_u32_f32_e32 v2, v2
	s_nop 0
	v_readfirstlane_b32 s23, v2
	s_mul_i32 s22, s22, s23
	s_mul_hi_u32 s22, s23, s22
	s_add_i32 s23, s23, s22
	s_mul_hi_u32 s22, s18, s23
	s_mul_i32 s22, s22, s21
	s_sub_i32 s18, s18, s22
	s_sub_i32 s22, s18, s21
	s_cmp_ge_u32 s18, s21
	s_cselect_b32 s18, s22, s18
	s_sub_i32 s22, s18, s21
	s_cmp_ge_u32 s18, s21
	s_cselect_b32 s18, s22, s18
	s_xor_b32 s18, s18, s19
	s_sub_i32 s18, s18, s19
	s_add_i32 s20, s20, s18
	v_lshl_or_b32 v2, s20, 8, v0
	v_ashrrev_i32_e32 v3, 31, v2
	v_lshl_add_u64 v[2:3], v[2:3], 2, s[6:7]
	global_load_dword v202, v[2:3], off

.LBB0_235:
	s_and_saveexec_b64 s[14:15], s[4:5]
	s_cbranch_execz .LBB0_237
	s_ashr_i32 s18, s18, 3
	s_add_i32 s18, s19, s18
	s_ashr_i32 s19, s18, 31
	s_lshr_b32 s19, s19, 26
	s_add_i32 s19, s18, s19
	s_ashr_i32 s20, s19, 6
	s_lshl_b32 s20, s20, 3
	s_sub_i32 s21, 0x80, s20
	s_min_i32 s21, s21, 8
	s_abs_i32 s21, s21
	v_cvt_f32_u32_e32 v4, s21
	s_sub_i32 s22, 0, s21
	s_andn2_b32 s19, s19, 63
	s_sub_i32 s18, s18, s19
	v_rcp_iflag_f32_e32 v4, v4
	s_ashr_i32 s19, s18, 31
	s_abs_i32 s18, s18
	v_mul_f32_e32 v4, 0x4f7ffffe, v4
	v_cvt_u32_f32_e32 v4, v4
	s_nop 0
	v_readfirstlane_b32 s23, v4
	s_mul_i32 s22, s22, s23
	s_mul_hi_u32 s22, s23, s22
	s_add_i32 s23, s23, s22
	s_mul_hi_u32 s22, s18, s23
	s_mul_i32 s22, s22, s21
	s_sub_i32 s18, s18, s22
	s_sub_i32 s22, s18, s21
	s_cmp_ge_u32 s18, s21
	s_cselect_b32 s18, s22, s18
	s_sub_i32 s22, s18, s21
	s_cmp_ge_u32 s18, s21
	s_cselect_b32 s18, s22, s18
	s_xor_b32 s18, s18, s19
	s_sub_i32 s18, s18, s19
	s_add_i32 s20, s20, s18
	v_lshl_or_b32 v4, s20, 8, v0
	v_ashrrev_i32_e32 v5, 31, v4
	v_lshl_add_u64 v[4:5], v[4:5], 2, s[6:7]
	global_load_dword v203, v[4:5], off

.LBB0_243:
	s_and_saveexec_b64 s[14:15], s[4:5]
	s_cbranch_execz .LBB0_245
	s_ashr_i32 s18, s18, 3
	s_add_i32 s18, s19, s18
	s_ashr_i32 s19, s18, 31
	s_lshr_b32 s19, s19, 26
	s_add_i32 s19, s18, s19
	s_ashr_i32 s20, s19, 6
	s_lshl_b32 s20, s20, 3
	s_sub_i32 s21, 0x80, s20
	s_min_i32 s21, s21, 8
	s_abs_i32 s21, s21
	v_cvt_f32_u32_e32 v2, s21
	s_sub_i32 s22, 0, s21
	s_andn2_b32 s19, s19, 63
	s_sub_i32 s18, s18, s19
	v_rcp_iflag_f32_e32 v2, v2
	s_ashr_i32 s19, s18, 31
	s_abs_i32 s18, s18
	v_mul_f32_e32 v2, 0x4f7ffffe, v2
	v_cvt_u32_f32_e32 v2, v2
	s_nop 0
	v_readfirstlane_b32 s23, v2
	s_mul_i32 s22, s22, s23
	s_mul_hi_u32 s22, s23, s22
	s_add_i32 s23, s23, s22
	s_mul_hi_u32 s22, s18, s23
	s_mul_i32 s22, s22, s21
	s_sub_i32 s18, s18, s22
	s_sub_i32 s22, s18, s21
	s_cmp_ge_u32 s18, s21
	s_cselect_b32 s18, s22, s18
	s_sub_i32 s22, s18, s21
	s_cmp_ge_u32 s18, s21
	s_cselect_b32 s18, s22, s18
	s_xor_b32 s18, s18, s19
	s_sub_i32 s18, s18, s19
	s_add_i32 s20, s20, s18
	v_lshl_or_b32 v2, s20, 8, v0
	v_ashrrev_i32_e32 v3, 31, v2
	v_lshl_add_u64 v[2:3], v[2:3], 2, s[6:7]
	global_load_dword v204, v[2:3], off

.LBB0_251:
	s_and_saveexec_b64 s[14:15], s[4:5]
	s_cbranch_execz .LBB0_253
	s_ashr_i32 s18, s18, 3
	s_add_i32 s18, s19, s18
	s_ashr_i32 s19, s18, 31
	s_lshr_b32 s19, s19, 26
	s_add_i32 s19, s18, s19
	s_ashr_i32 s20, s19, 6
	s_lshl_b32 s20, s20, 3
	s_sub_i32 s21, 0x80, s20
	s_min_i32 s21, s21, 8
	s_abs_i32 s21, s21
	v_cvt_f32_u32_e32 v4, s21
	s_sub_i32 s22, 0, s21
	s_andn2_b32 s19, s19, 63
	s_sub_i32 s18, s18, s19
	v_rcp_iflag_f32_e32 v4, v4
	s_ashr_i32 s19, s18, 31
	s_abs_i32 s18, s18
	v_mul_f32_e32 v4, 0x4f7ffffe, v4
	v_cvt_u32_f32_e32 v4, v4
	s_nop 0
	v_readfirstlane_b32 s23, v4
	s_mul_i32 s22, s22, s23
	s_mul_hi_u32 s22, s23, s22
	s_add_i32 s23, s23, s22
	s_mul_hi_u32 s22, s18, s23
	s_mul_i32 s22, s22, s21
	s_sub_i32 s18, s18, s22
	s_sub_i32 s22, s18, s21
	s_cmp_ge_u32 s18, s21
	s_cselect_b32 s18, s22, s18
	s_sub_i32 s22, s18, s21
	s_cmp_ge_u32 s18, s21
	s_cselect_b32 s18, s22, s18
	s_xor_b32 s18, s18, s19
	s_sub_i32 s18, s18, s19
	s_add_i32 s20, s20, s18
	v_lshl_or_b32 v4, s20, 8, v0
	v_ashrrev_i32_e32 v5, 31, v4
	v_lshl_add_u64 v[4:5], v[4:5], 2, s[6:7]
	global_load_dword v205, v[4:5], off

.LBB0_259:
	s_and_saveexec_b64 s[14:15], s[4:5]
	s_cbranch_execz .LBB0_261
	s_ashr_i32 s18, s18, 3
	s_add_i32 s18, s19, s18
	s_ashr_i32 s19, s18, 31
	s_lshr_b32 s19, s19, 26
	s_add_i32 s19, s18, s19
	s_ashr_i32 s20, s19, 6
	s_lshl_b32 s20, s20, 3
	s_sub_i32 s21, 0x80, s20
	s_min_i32 s21, s21, 8
	s_abs_i32 s21, s21
	v_cvt_f32_u32_e32 v2, s21
	s_sub_i32 s22, 0, s21
	s_andn2_b32 s19, s19, 63
	s_sub_i32 s18, s18, s19
	v_rcp_iflag_f32_e32 v2, v2
	s_ashr_i32 s19, s18, 31
	s_abs_i32 s18, s18
	v_mul_f32_e32 v2, 0x4f7ffffe, v2
	v_cvt_u32_f32_e32 v2, v2
	s_nop 0
	v_readfirstlane_b32 s23, v2
	s_mul_i32 s22, s22, s23
	s_mul_hi_u32 s22, s23, s22
	s_add_i32 s23, s23, s22
	s_mul_hi_u32 s22, s18, s23
	s_mul_i32 s22, s22, s21
	s_sub_i32 s18, s18, s22
	s_sub_i32 s22, s18, s21
	s_cmp_ge_u32 s18, s21
	s_cselect_b32 s18, s22, s18
	s_sub_i32 s22, s18, s21
	s_cmp_ge_u32 s18, s21
	s_cselect_b32 s18, s22, s18
	s_xor_b32 s18, s18, s19
	s_sub_i32 s18, s18, s19
	s_add_i32 s20, s20, s18
	v_lshl_or_b32 v2, s20, 8, v0
	v_ashrrev_i32_e32 v3, 31, v2
	v_lshl_add_u64 v[2:3], v[2:3], 2, s[6:7]
	global_load_dword v206, v[2:3], off

.LBB0_267:
	s_and_saveexec_b64 s[12:13], s[4:5]
	s_cbranch_execz .LBB0_269
	s_ashr_i32 s4, s14, 3
	s_add_i32 s4, s15, s4
	s_ashr_i32 s5, s4, 31
	s_lshr_b32 s5, s5, 26
	s_add_i32 s5, s4, s5
	s_ashr_i32 s14, s5, 6
	s_lshl_b32 s14, s14, 3
	s_sub_i32 s15, 0x80, s14
	s_min_i32 s15, s15, 8
	s_abs_i32 s15, s15
	v_cvt_f32_u32_e32 v2, s15
	s_sub_i32 s18, 0, s15
	s_andn2_b32 s5, s5, 63
	s_sub_i32 s4, s4, s5
	v_rcp_iflag_f32_e32 v2, v2
	s_ashr_i32 s5, s4, 31
	s_abs_i32 s4, s4
	v_mul_f32_e32 v2, 0x4f7ffffe, v2
	v_cvt_u32_f32_e32 v2, v2
	s_nop 0
	v_readfirstlane_b32 s19, v2
	s_mul_i32 s18, s18, s19
	s_mul_hi_u32 s18, s19, s18
	s_add_i32 s19, s19, s18
	s_mul_hi_u32 s18, s4, s19
	s_mul_i32 s18, s18, s15
	s_sub_i32 s4, s4, s18
	s_sub_i32 s18, s4, s15
	s_cmp_ge_u32 s4, s15
	s_cselect_b32 s4, s18, s4
	s_sub_i32 s18, s4, s15
	s_cmp_ge_u32 s4, s15
	s_cselect_b32 s4, s18, s4
	s_xor_b32 s4, s4, s5
	s_sub_i32 s4, s4, s5
	s_add_i32 s14, s14, s4
	v_lshl_or_b32 v2, s14, 8, v0
	v_ashrrev_i32_e32 v3, 31, v2
	v_lshl_add_u64 v[2:3], v[2:3], 2, s[6:7]
	global_load_dword v207, v[2:3], off

.LBB0_270:
	v_readfirstlane_b32 s18, v0
	s_and_b64 vcc, exec, s[10:11]
	s_and_saveexec_b64 s[12:13], s[4:5]
	s_waitcnt vmcnt(0)
	ds_write_b32 v1, v200
	ds_write_b32 v1, v201 offset:1024
	ds_write_b32 v1, v202 offset:2048
	ds_write_b32 v1, v203 offset:3072
	ds_write_b32 v1, v204 offset:4096
	ds_write_b32 v1, v205 offset:5120
	ds_write_b32 v1, v206 offset:6144
	ds_write_b32 v1, v207 offset:7168
	s_or_b64 exec, exec, s[12:13]
	s_waitcnt lgkmcnt(0)
	s_barrier
	s_cbranch_vccz .LBB0_276
	s_lshr_b32 s4, s59, 29
	s_add_i32 s6, s2, s4
	s_and_b32 s4, s6, -8
	s_sub_i32 s7, s2, s4
	s_cmp_gt_i32 s7, -1
	s_cbranch_scc0 .LBB0_273
	s_lshl_b32 s12, s7, 7
	s_cbranch_execz .LBB0_274
	s_branch .LBB0_275
